# ret_local items: next item's K/V staging loads prefetched into registers during the current item's compute (consecutive ret_local iterations)
# speedup vs baseline: 1.0085x; 1.0085x over previous
.LBB0_549:
	s_andn2_b64 vcc, exec, s[0:1]
	s_cbranch_vccnz .LBB0_551
	v_readlane_b32 s1, v244, 58
	s_add_i32 s0, s1, 0xfffffd00
	s_bfe_u32 s1, s1, 0x30005
	v_cvt_f32_ubyte0_e32 v0, s1
	v_sub_f32_e32 v0, 0xc0a00000, v0
	s_mov_b32 s4, 0xc2fc0000
	v_cmp_gt_f32_e32 vcc, s4, v0
	s_and_b64 s[4:5], vcc, exec
	s_cselect_b32 s4, 0xffffffc0, 0
	v_cndmask_b32_e32 v1, 0, v201, vcc
	v_add_f32_e32 v0, v0, v1
	v_exp_f32_e32 v0, v0
	s_lshl_b32 s5, s0, 7
	s_and_b32 s5, s5, 0xf80
	s_lshl_b32 s16, s1, 7
	v_ldexp_f32 v0, v0, s4
	s_lshl_b32 s4, s0, 4
	s_and_b32 s4, s4, 0x7000
	v_sub_f32_e32 v0, 1.0, v0
	s_or_b32 s4, s4, s5
	v_log_f32_e32 v16, v0
	v_or_b32_e32 v0, s4, v44
	v_lshl_add_u64 v[8:9], v[68:69], 0, s[16:17]
	v_lshlrev_b32_e32 v42, 10, v0
	v_lshl_add_u64 v[0:1], v[8:9], 0, v[42:43]
	v_lshl_add_u64 v[10:11], v[70:71], 0, s[16:17]
	v_lshl_add_u64 v[4:5], v[10:11], 0, v[42:43]
	v_add_lshl_u32 v42, s4, v46, 10
	v_lshl_add_u64 v[94:95], v[8:9], 0, v[42:43]
	v_lshl_add_u64 v[120:121], v[10:11], 0, v[42:43]
	s_mov_b64 s[8:9], 0x400000
	v_lshl_add_u64 v[112:113], v[0:1], 0, s[8:9]
	v_lshl_add_u64 v[114:115], v[4:5], 0, s[8:9]
	v_lshl_add_u64 v[116:117], v[94:95], 0, s[8:9]
	v_lshl_add_u64 v[118:119], v[120:121], 0, s[8:9]
	s_lshl_b32 s16, s0, 12
	s_lshl_b64 s[0:1], s[16:17], 2
	v_readlane_b32 s4, v244, 42
	s_add_u32 s0, s4, s0
	v_readlane_b32 s4, v244, 43
	s_addc_u32 s1, s4, s1
	v_readlane_b32 s7, v244, 58
	v_readlane_b32 s12, v246, 60
	s_nop 0
	s_bfe_u32 s13, s12, 0x40003
	s_lshl_b32 s13, s13, 8
	s_add_i32 s12, s12, s13
	s_cmp_lg_u32 s7, s12
	s_cselect_b32 s13, 1, 0
	s_cmpk_gt_u32 s7, 0x3ff
	s_cselect_b32 s14, 1, 0
	s_and_b32 s13, s13, s14
	s_barrier
	s_cmp_lg_u32 s13, 0
	s_cbranch_scc1 .Lrl_pf
	global_load_dwordx4 v[0:3], v[0:1], off
	global_load_dwordx4 v[4:7], v[4:5], off
	global_load_dwordx4 v[86:89], v[94:95], off
	global_load_dwordx4 v[90:93], v[120:121], off
	v_mul_f32_e32 v12, v16, v142
	v_exp_f32_e32 v12, v12
	s_waitcnt vmcnt(3)
	v_lshlrev_b32_e32 v14, 16, v0
	v_and_b32_e32 v15, 0xffff0000, v0
	v_pk_mul_f32 v[14:15], v[12:13], v[14:15] op_sel_hi:[0,1]
	v_cvt_pk_bf16_f32 v0, v14, v15
	v_lshlrev_b32_e32 v14, 16, v1
	v_and_b32_e32 v15, 0xffff0000, v1
	v_pk_mul_f32 v[14:15], v[12:13], v[14:15] op_sel_hi:[0,1]
	v_cvt_pk_bf16_f32 v1, v14, v15
	v_lshlrev_b32_e32 v14, 16, v2
	v_and_b32_e32 v15, 0xffff0000, v2
	v_pk_mul_f32 v[14:15], v[12:13], v[14:15] op_sel_hi:[0,1]
	v_cvt_pk_bf16_f32 v2, v14, v15
	v_lshlrev_b32_e32 v14, 16, v3
	v_and_b32_e32 v15, 0xffff0000, v3
	v_pk_mul_f32 v[12:13], v[12:13], v[14:15] op_sel_hi:[0,1]
	v_cvt_pk_bf16_f32 v3, v12, v13
	v_add_u32_e32 v12, v141, v143
	ds_write_b128 v12, v[0:3]
	s_waitcnt vmcnt(2)
	ds_write_b128 v12, v[4:7] offset:18432
	v_mul_f32_e32 v8, v16, v144
	v_exp_f32_e32 v8, v8
	s_waitcnt vmcnt(1)
	v_mov_b32_e32 v0, v86
	v_mov_b32_e32 v1, v87
	v_mov_b32_e32 v2, v88
	v_mov_b32_e32 v3, v89
	v_lshlrev_b32_e32 v10, 16, v0
	v_and_b32_e32 v11, 0xffff0000, v0
	v_pk_mul_f32 v[10:11], v[8:9], v[10:11] op_sel_hi:[0,1]
	v_cvt_pk_bf16_f32 v0, v10, v11
	v_lshlrev_b32_e32 v10, 16, v1
	v_and_b32_e32 v11, 0xffff0000, v1
	v_pk_mul_f32 v[10:11], v[8:9], v[10:11] op_sel_hi:[0,1]
	v_cvt_pk_bf16_f32 v1, v10, v11
	v_lshlrev_b32_e32 v10, 16, v2
	v_and_b32_e32 v11, 0xffff0000, v2
	v_pk_mul_f32 v[10:11], v[8:9], v[10:11] op_sel_hi:[0,1]
	v_cvt_pk_bf16_f32 v2, v10, v11
	v_lshlrev_b32_e32 v10, 16, v3
	v_and_b32_e32 v11, 0xffff0000, v3
	v_pk_mul_f32 v[8:9], v[8:9], v[10:11] op_sel_hi:[0,1]
	v_cvt_pk_bf16_f32 v3, v8, v9
	v_add_u32_e32 v8, v141, v145
	ds_write_b128 v8, v[0:3]
	s_waitcnt vmcnt(0)
	ds_write_b128 v8, v[90:93] offset:18432
	s_branch .Lrl_join
.Lrl_pf:
	s_waitcnt vmcnt(8)
	v_mul_f32_e32 v12, v16, v142
	v_exp_f32_e32 v12, v12
	v_mov_b32_e32 v0, v96
	v_mov_b32_e32 v1, v97
	v_mov_b32_e32 v2, v98
	v_mov_b32_e32 v3, v99
	v_lshlrev_b32_e32 v14, 16, v0
	v_and_b32_e32 v15, 0xffff0000, v0
	v_pk_mul_f32 v[14:15], v[12:13], v[14:15] op_sel_hi:[0,1]
	v_cvt_pk_bf16_f32 v0, v14, v15
	v_lshlrev_b32_e32 v14, 16, v1
	v_and_b32_e32 v15, 0xffff0000, v1
	v_pk_mul_f32 v[14:15], v[12:13], v[14:15] op_sel_hi:[0,1]
	v_cvt_pk_bf16_f32 v1, v14, v15
	v_lshlrev_b32_e32 v14, 16, v2
	v_and_b32_e32 v15, 0xffff0000, v2
	v_pk_mul_f32 v[14:15], v[12:13], v[14:15] op_sel_hi:[0,1]
	v_cvt_pk_bf16_f32 v2, v14, v15
	v_lshlrev_b32_e32 v14, 16, v3
	v_and_b32_e32 v15, 0xffff0000, v3
	v_pk_mul_f32 v[12:13], v[12:13], v[14:15] op_sel_hi:[0,1]
	v_cvt_pk_bf16_f32 v3, v12, v13
	v_add_u32_e32 v12, v141, v143
	ds_write_b128 v12, v[0:3]
	ds_write_b128 v12, v[100:103] offset:18432
	v_mul_f32_e32 v8, v16, v144
	v_exp_f32_e32 v8, v8
	v_mov_b32_e32 v0, v104
	v_mov_b32_e32 v1, v105
	v_mov_b32_e32 v2, v106
	v_mov_b32_e32 v3, v107
	v_lshlrev_b32_e32 v10, 16, v0
	v_and_b32_e32 v11, 0xffff0000, v0
	v_pk_mul_f32 v[10:11], v[8:9], v[10:11] op_sel_hi:[0,1]
	v_cvt_pk_bf16_f32 v0, v10, v11
	v_lshlrev_b32_e32 v10, 16, v1
	v_and_b32_e32 v11, 0xffff0000, v1
	v_pk_mul_f32 v[10:11], v[8:9], v[10:11] op_sel_hi:[0,1]
	v_cvt_pk_bf16_f32 v1, v10, v11
	v_lshlrev_b32_e32 v10, 16, v2
	v_and_b32_e32 v11, 0xffff0000, v2
	v_pk_mul_f32 v[10:11], v[8:9], v[10:11] op_sel_hi:[0,1]
	v_cvt_pk_bf16_f32 v2, v10, v11
	v_lshlrev_b32_e32 v10, 16, v3
	v_and_b32_e32 v11, 0xffff0000, v3
	v_pk_mul_f32 v[8:9], v[8:9], v[10:11] op_sel_hi:[0,1]
	v_cvt_pk_bf16_f32 v3, v8, v9
	v_add_u32_e32 v8, v141, v145
	ds_write_b128 v8, v[0:3]
	ds_write_b128 v8, v[108:111] offset:18432
.Lrl_join:
	s_waitcnt lgkmcnt(0)
	s_barrier
	s_cmpk_lt_u32 s7, 0xa00
	s_cbranch_scc0 .Lrl_nopf
	global_load_dwordx4 v[96:99], v[112:113], off
	global_load_dwordx4 v[100:103], v[114:115], off
	global_load_dwordx4 v[104:107], v[116:117], off
	global_load_dwordx4 v[108:111], v[118:119], off
.Lrl_nopf:
	ds_read_b64_tr_b16 v[0:1], v185 offset:18432
	ds_read_b64_tr_b16 v[2:3], v185 offset:19008
	ds_read_b64_tr_b16 v[6:7], v186 offset:576
	ds_read_b64_tr_b16 v[4:5], v186
	ds_read_b64_tr_b16 v[8:9], v186 offset:32
	ds_read_b64_tr_b16 v[10:11], v186 offset:608
	s_waitcnt lgkmcnt(2)
	v_mfma_f32_16x16x32_bf16 v[4:7], v[0:3], v[4:7], 0
	s_waitcnt lgkmcnt(0)
	v_mfma_f32_16x16x32_bf16 v[0:3], v[0:3], v[8:11], 0
	ds_read_b64_tr_b16 v[8:9], v185 offset:23040
	ds_read_b64_tr_b16 v[10:11], v185 offset:23616
	ds_read_b64_tr_b16 v[12:13], v186 offset:4608
	ds_read_b64_tr_b16 v[14:15], v186 offset:5184
	s_waitcnt lgkmcnt(0)
	v_mfma_f32_16x16x32_bf16 v[4:7], v[8:11], v[12:15], v[4:7]
	ds_read_b64_tr_b16 v[12:13], v186 offset:4640
	ds_read_b64_tr_b16 v[14:15], v186 offset:5216
	s_waitcnt lgkmcnt(0)
	v_mfma_f32_16x16x32_bf16 v[0:3], v[8:11], v[12:15], v[0:3]
	ds_read_b64_tr_b16 v[8:9], v185 offset:27648
	ds_read_b64_tr_b16 v[10:11], v185 offset:28224
	ds_read_b64_tr_b16 v[12:13], v186 offset:9216
	ds_read_b64_tr_b16 v[14:15], v186 offset:9792
	s_waitcnt lgkmcnt(0)
	v_mfma_f32_16x16x32_bf16 v[4:7], v[8:11], v[12:15], v[4:7]
	ds_read_b64_tr_b16 v[12:13], v186 offset:9248
	ds_read_b64_tr_b16 v[14:15], v186 offset:9824
	s_waitcnt lgkmcnt(0)
	v_mfma_f32_16x16x32_bf16 v[0:3], v[8:11], v[12:15], v[0:3]
	ds_read_b64_tr_b16 v[8:9], v185 offset:32256
	ds_read_b64_tr_b16 v[10:11], v185 offset:32832
	ds_read_b64_tr_b16 v[12:13], v186 offset:13824
	ds_read_b64_tr_b16 v[14:15], v186 offset:14400
	s_waitcnt lgkmcnt(0)
	v_mfma_f32_16x16x32_bf16 v[4:7], v[8:11], v[12:15], v[4:7]
	ds_read_b64_tr_b16 v[12:13], v186 offset:13856
	ds_read_b64_tr_b16 v[14:15], v186 offset:14432
	s_waitcnt lgkmcnt(0)
	v_mfma_f32_16x16x32_bf16 v[0:3], v[8:11], v[12:15], v[0:3]
	v_lshl_add_u64 v[8:9], v[48:49], 2, s[0:1]
	s_nop 2
	global_store_dword v[8:9], v4, off
	global_store_dword v[8:9], v5, off offset:256
	global_store_dword v[8:9], v6, off offset:512
	global_store_dword v[8:9], v7, off offset:768
	global_store_dword v[8:9], v0, off offset:64
	v_lshl_add_u64 v[4:5], v[78:79], 2, s[0:1]
	global_store_dword v[4:5], v1, off offset:256
	global_store_dword v[4:5], v2, off offset:512
	global_store_dword v[4:5], v3, off offset:768
